# P2 side work: MLA cache f32->bf16 conversion loop rewritten with 4 elements per trip (8 loads in flight) instead of one load-wait-store per trip
# speedup vs baseline: 1.0083x; 1.0083x over previous
.LBB0_521:
	s_or_b64 exec, exec, s[8:9]
	s_mov_b32 s7, 0
	v_mov_b32_e32 v0, v250
	s_lshl_b64 s[0:1], s[6:7], 9
	s_mov_b32 s5, s7
	v_ashrrev_i32_e32 v1, 31, v0
	v_lshl_add_u64 v[4:5], s[0:1], 0, v[0:1]
	s_lshl_b64 s[0:1], s[4:5], 9
	s_mov_b64 s[10:11], 0x480000
	s_add_u32 s8, s50, 0x131ed700
	v_cmp_gt_u64_e32 vcc, s[10:11], v[4:5]
	v_readlane_b32 s10, v254, 50
	s_addc_u32 s9, s51, 0
	v_readlane_b32 s11, v254, 51
	v_lshl_add_u32 v14, s10, 9, v0
	s_and_saveexec_b64 s[10:11], vcc
	s_cbranch_execz .LBB0_528
	s_mov_b32 s14, 0x38e38e39
	s_lshl_b32 s3, s0, 1
	s_add_i32 s4, s3, s0
	s_lshl_b32 s5, s0, 2
	s_mov_b32 s12, 0x480000
	v_mov_b32_e32 v8, v4
	v_mov_b32_e32 v92, s80
	v_mov_b32_e32 v93, s81
	v_mov_b32_e32 v94, s82
	v_mov_b32_e32 v95, s83
.Lcv_loop:
	v_mov_b32_e32 v30, v8
	v_mul_hi_u32 v26, v30, s14
	v_lshrrev_b32_e32 v26, 4, v26
	v_mul_u32_u24_e32 v27, 0x48, v26
	v_sub_u32_e32 v27, v30, v27
	v_cmp_lt_u32_e64 s[22:23], 63, v27
	v_lshlrev_b32_e32 v28, 11, v26
	v_lshlrev_b32_e32 v29, 8, v26
	v_lshl_add_u32 v28, v27, 5, v28
	v_lshl_add_u32 v29, v27, 5, v29
	v_add_u32_e32 v29, 0xfffff800, v29
	v_cndmask_b32_e64 v28, v28, v29, s[22:23]
	v_cndmask_b32_e64 v29, v92, v94, s[22:23]
	v_cndmask_b32_e64 v33, v93, v95, s[22:23]
	v_add_co_u32_e32 v32, vcc, v29, v28
	v_lshrrev_b32_e32 v28, 12, v26
	v_lshl_add_u32 v28, v28, 6, v26
	v_addc_co_u32_e32 v33, vcc, 0, v33, vcc
	v_mul_u32_u24_e32 v28, 0x480, v28
	v_lshl_add_u32 v42, v27, 4, v28
	v_cmp_gt_u32_e32 vcc, s12, v30
	s_and_saveexec_b64 s[18:19], vcc
	global_load_dwordx4 v[34:37], v[32:33], off
	global_load_dwordx4 v[38:41], v[32:33], off offset:16
	s_mov_b64 exec, s[18:19]
	v_add_u32_e32 v44, s0, v8
	v_mul_hi_u32 v26, v44, s14
	v_lshrrev_b32_e32 v26, 4, v26
	v_mul_u32_u24_e32 v27, 0x48, v26
	v_sub_u32_e32 v27, v44, v27
	v_cmp_lt_u32_e64 s[22:23], 63, v27
	v_lshlrev_b32_e32 v28, 11, v26
	v_lshlrev_b32_e32 v29, 8, v26
	v_lshl_add_u32 v28, v27, 5, v28
	v_lshl_add_u32 v29, v27, 5, v29
	v_add_u32_e32 v29, 0xfffff800, v29
	v_cndmask_b32_e64 v28, v28, v29, s[22:23]
	v_cndmask_b32_e64 v29, v92, v94, s[22:23]
	v_cndmask_b32_e64 v47, v93, v95, s[22:23]
	v_add_co_u32_e32 v46, vcc, v29, v28
	v_lshrrev_b32_e32 v28, 12, v26
	v_lshl_add_u32 v28, v28, 6, v26
	v_addc_co_u32_e32 v47, vcc, 0, v47, vcc
	v_mul_u32_u24_e32 v28, 0x480, v28
	v_lshl_add_u32 v56, v27, 4, v28
	v_cmp_gt_u32_e32 vcc, s12, v44
	s_and_saveexec_b64 s[18:19], vcc
	global_load_dwordx4 v[48:51], v[46:47], off
	global_load_dwordx4 v[52:55], v[46:47], off offset:16
	s_mov_b64 exec, s[18:19]
	v_add_u32_e32 v58, s3, v8
	v_mul_hi_u32 v26, v58, s14
	v_lshrrev_b32_e32 v26, 4, v26
	v_mul_u32_u24_e32 v27, 0x48, v26
	v_sub_u32_e32 v27, v58, v27
	v_cmp_lt_u32_e64 s[22:23], 63, v27
	v_lshlrev_b32_e32 v28, 11, v26
	v_lshlrev_b32_e32 v29, 8, v26
	v_lshl_add_u32 v28, v27, 5, v28
	v_lshl_add_u32 v29, v27, 5, v29
	v_add_u32_e32 v29, 0xfffff800, v29
	v_cndmask_b32_e64 v28, v28, v29, s[22:23]
	v_cndmask_b32_e64 v29, v92, v94, s[22:23]
	v_cndmask_b32_e64 v61, v93, v95, s[22:23]
	v_add_co_u32_e32 v60, vcc, v29, v28
	v_lshrrev_b32_e32 v28, 12, v26
	v_lshl_add_u32 v28, v28, 6, v26
	v_addc_co_u32_e32 v61, vcc, 0, v61, vcc
	v_mul_u32_u24_e32 v28, 0x480, v28
	v_lshl_add_u32 v70, v27, 4, v28
	v_cmp_gt_u32_e32 vcc, s12, v58
	s_and_saveexec_b64 s[18:19], vcc
	global_load_dwordx4 v[62:65], v[60:61], off
	global_load_dwordx4 v[66:69], v[60:61], off offset:16
	s_mov_b64 exec, s[18:19]
	v_add_u32_e32 v72, s4, v8
	v_mul_hi_u32 v26, v72, s14
	v_lshrrev_b32_e32 v26, 4, v26
	v_mul_u32_u24_e32 v27, 0x48, v26
	v_sub_u32_e32 v27, v72, v27
	v_cmp_lt_u32_e64 s[22:23], 63, v27
	v_lshlrev_b32_e32 v28, 11, v26
	v_lshlrev_b32_e32 v29, 8, v26
	v_lshl_add_u32 v28, v27, 5, v28
	v_lshl_add_u32 v29, v27, 5, v29
	v_add_u32_e32 v29, 0xfffff800, v29
	v_cndmask_b32_e64 v28, v28, v29, s[22:23]
	v_cndmask_b32_e64 v29, v92, v94, s[22:23]
	v_cndmask_b32_e64 v75, v93, v95, s[22:23]
	v_add_co_u32_e32 v74, vcc, v29, v28
	v_lshrrev_b32_e32 v28, 12, v26
	v_lshl_add_u32 v28, v28, 6, v26
	v_addc_co_u32_e32 v75, vcc, 0, v75, vcc
	v_mul_u32_u24_e32 v28, 0x480, v28
	v_lshl_add_u32 v84, v27, 4, v28
	v_cmp_gt_u32_e32 vcc, s12, v72
	s_and_saveexec_b64 s[18:19], vcc
	global_load_dwordx4 v[76:79], v[74:75], off
	global_load_dwordx4 v[80:83], v[74:75], off offset:16
	s_mov_b64 exec, s[18:19]
	s_waitcnt vmcnt(6)
	v_cvt_pk_bf16_f32 v34, v34, v35
	v_cvt_pk_bf16_f32 v35, v36, v37
	v_cvt_pk_bf16_f32 v36, v38, v39
	v_cvt_pk_bf16_f32 v37, v40, v41
	v_cmp_gt_u32_e32 vcc, s12, v30
	s_and_saveexec_b64 s[18:19], vcc
	global_store_dwordx4 v42, v[34:37], s[8:9]
	s_mov_b64 exec, s[18:19]
	s_waitcnt vmcnt(5)
	v_cvt_pk_bf16_f32 v48, v48, v49
	v_cvt_pk_bf16_f32 v49, v50, v51
	v_cvt_pk_bf16_f32 v50, v52, v53
	v_cvt_pk_bf16_f32 v51, v54, v55
	v_cmp_gt_u32_e32 vcc, s12, v44
	s_and_saveexec_b64 s[18:19], vcc
	global_store_dwordx4 v56, v[48:51], s[8:9]
	s_mov_b64 exec, s[18:19]
	s_waitcnt vmcnt(4)
	v_cvt_pk_bf16_f32 v62, v62, v63
	v_cvt_pk_bf16_f32 v63, v64, v65
	v_cvt_pk_bf16_f32 v64, v66, v67
	v_cvt_pk_bf16_f32 v65, v68, v69
	v_cmp_gt_u32_e32 vcc, s12, v58
	s_and_saveexec_b64 s[18:19], vcc
	global_store_dwordx4 v70, v[62:65], s[8:9]
	s_mov_b64 exec, s[18:19]
	s_waitcnt vmcnt(3)
	v_cvt_pk_bf16_f32 v76, v76, v77
	v_cvt_pk_bf16_f32 v77, v78, v79
	v_cvt_pk_bf16_f32 v78, v80, v81
	v_cvt_pk_bf16_f32 v79, v82, v83
	v_cmp_gt_u32_e32 vcc, s12, v72
	s_and_saveexec_b64 s[18:19], vcc
	global_store_dwordx4 v84, v[76:79], s[8:9]
	s_mov_b64 exec, s[18:19]
	v_add_u32_e32 v8, s5, v8
	v_cmp_gt_u32_e32 vcc, s12, v8
	s_cbranch_vccnz .Lcv_loop
